# scan item prologue: the five per-head constant loads issued together with one wait (was three serial load/wait round trips)
# speedup vs baseline: 1.0023x; 1.0023x over previous
; DI void scan_item(const Params& p, int b, int h, int half, char* smem, unsigned* pgen, unsigned kp) {
;     ...
;   __syncthreads();
;   if (tid < 64) {
;     CT[tid] = p.mu[h * 64 + tid]; CT[64 + tid] = p.mu[1024 + h * 64 + tid]; CT[128 + tid] = p.r_k[h * 64 + tid];
;     CT[192 + tid] = p.lnx_w[h * 64 + tid]; CT[256 + tid] = p.lnx_b[h * 64 + tid];
;   }
.LBB0_681:
	s_ashr_i32 s10, s21, 1
	s_lshl_b32 s4, s10, 6
	s_barrier
	s_mov_b64 s[16:17], exec
	v_readlane_b32 s18, v254, 32
	v_readlane_b32 s19, v254, 33
	s_and_b64 s[18:19], s[16:17], s[18:19]
	s_mov_b64 exec, s[18:19]
	s_cbranch_execz .LBB0_683
	v_or_b32_e32 v2, s4, v173
	v_ashrrev_i32_e32 v3, 31, v2
	v_lshlrev_b64 v[2:3], 2, v[2:3]
	v_lshl_add_u64 v[4:5], s[72:73], 0, v[2:3]
	global_load_dword v0, v[4:5], off
	v_add_u32_e32 v4, s4, v187
	v_ashrrev_i32_e32 v5, 31, v4
	v_lshl_add_u64 v[4:5], v[4:5], 2, s[72:73]
	global_load_dword v154, v[4:5], off
	v_readlane_b32 s36, v252, 20
	v_readlane_b32 s48, v252, 32
	v_readlane_b32 s49, v252, 33
	v_readlane_b32 s50, v252, 34
	v_readlane_b32 s51, v252, 35
	v_readlane_b32 s24, v252, 6
	v_readlane_b32 s25, v252, 7
	v_readlane_b32 s37, v252, 21
	v_readlane_b32 s38, v252, 22
	v_readlane_b32 s39, v252, 23
	v_readlane_b32 s40, v252, 24
	v_readlane_b32 s41, v252, 25
	v_readlane_b32 s42, v252, 26
	v_readlane_b32 s43, v252, 27
	v_readlane_b32 s44, v252, 28
	v_readlane_b32 s45, v252, 29
	v_readlane_b32 s46, v252, 30
	v_readlane_b32 s47, v252, 31
	v_readlane_b32 s26, v252, 8
	v_readlane_b32 s27, v252, 9
	v_readlane_b32 s28, v252, 10
	v_readlane_b32 s29, v252, 11
	v_readlane_b32 s30, v252, 12
	v_readlane_b32 s31, v252, 13
	v_lshl_add_u64 v[4:5], s[48:49], 0, v[2:3]
	global_load_dword v155, v[4:5], off
	v_lshl_add_u64 v[4:5], s[50:51], 0, v[2:3]
	global_load_dword v156, v[4:5], off
	v_lshl_add_u64 v[2:3], s[24:25], 0, v[2:3]
	global_load_dword v157, v[2:3], off
	s_waitcnt vmcnt(0)
	ds_write2st64_b32 v166, v0, v154 offset0:113 offset1:114
	ds_write2st64_b32 v166, v155, v156 offset0:115 offset1:116
	ds_write_b32 v166, v157 offset:29952
